# closed-form tile coordinates also in the retention and stick-breaking in-projection GEMM phases
# speedup vs baseline: 1.0102x; 1.0013x over previous
;     __device__ bool next(int i, pg8::Unit& u) const { const int cnt = (nwg - c + G - 1) / G; if (i >= reps * cnt) return false; return pg8::StaticOrder::next(i % cnt, u); }
;     __host__ __device__ bool next(int i, Unit& u) const {
;         const long L = (long)i * G + c; if (L >= nwg) return false;
;         int wgid = (int)L; { const int q = nwg / NXCD, r = nwg % NXCD, xcd = wgid % NXCD, off = wgid / NXCD; wgid = (xcd < r ? xcd * (q + 1) : r * (q + 1) + (xcd - r) * q) + off; }
;         const int nig = WGM * nN, gid = wgid / nig, fm = gid * WGM, gsz = (nM - fm) < WGM ? (nM - fm) : WGM;
;         u.pm = fm + ((wgid % nig) % gsz); u.pn = (wgid % nig) / gsz; return true;
.LBB0_487:
	s_add_i32 s42, s42, 1
	s_cmp_ge_i32 s42, s15
	s_mov_b64 s[22:23], 0
	s_cbranch_scc1 .LBB0_490
	s_mul_hi_u32 s0, s42, s67
	s_mul_i32 s0, s0, s15
	s_sub_i32 s0, s42, s0
	s_sub_i32 s1, s0, s15
	s_cmp_ge_u32 s0, s15
	s_cselect_b32 s0, s1, s0
	s_sub_i32 s1, s0, s15
	s_cmp_ge_u32 s0, s15
	s_cselect_b32 s0, s1, s0
	s_mul_i32 s1, s0, s64
	s_mul_hi_u32 s5, s0, s88
	s_add_i32 s5, s5, s1
	s_mul_i32 s0, s0, s88
	s_add_u32 s0, s0, s89
	s_addc_u32 s1, s5, s65
	v_mov_b64_e32 v[0:1], 0x17ff
	v_cmp_gt_i64_e32 vcc, s[0:1], v[0:1]
	s_cbranch_vccnz .LBB0_490
	s_ashr_i32 s1, s0, 31
	s_lshr_b32 s1, s1, 29
	s_add_i32 s1, s0, s1
	s_ashr_i32 s5, s1, 3
	s_and_b32 s1, s1, -8
	s_sub_i32 s0, s0, s1
	s_cmp_lt_i32 s0, 0
	s_movk_i32 s1, 0x301
	s_cselect_b32 s1, s1, 0x300
	s_mul_i32 s0, s0, s1
	s_add_i32 s0, s0, s5
	s_mul_hi_i32 s1, s0, 0x2aaaaaab
	s_lshr_b32 s5, s1, 31
	s_ashr_i32 s1, s1, 6
	s_add_i32 s1, s1, s5
	s_lshl_b32 s5, s1, 3
	s_mulk_i32 s1, 0x180
	s_sub_i32 s0, s0, s1
	s_lshr_b32 s18, s0, 3
	s_and_b32 s0, s0, 7
	s_add_i32 s20, s5, s0
	s_mov_b64 s[22:23], -1

;     __host__ __device__ bool next(int i, Unit& u) const {
;     ...
;         int wgid = (int)L; { const int q = nwg / NXCD, r = nwg % NXCD, xcd = wgid % NXCD, off = wgid / NXCD; wgid = (xcd < r ? xcd * (q + 1) : r * (q + 1) + (xcd - r) * q) + off; }
;         const int nig = WGM * nN, gid = wgid / nig, fm = gid * WGM, gsz = (nM - fm) < WGM ? (nM - fm) : WGM;
;         u.pm = fm + ((wgid % nig) % gsz); u.pn = (wgid % nig) / gsz; return true;
.LBB0_953:
	s_ashr_i32 s1, s1, 3
	s_add_i32 s1, s18, s1
	s_ashr_i32 s5, s1, 31
	s_lshr_b32 s5, s5, 24
	s_add_i32 s5, s1, s5
	s_ashr_i32 s16, s5, 8
	s_lshl_b32 s17, s16, 3
	s_and_b32 s5, s5, 0xffffff00
	s_sub_i32 s1, s1, s5
	s_mov_b64 s[62:63], -1
	s_lshr_b32 s40, s1, 3
	s_and_b32 s1, s1, 7
	s_add_i32 s52, s17, s1
